# v22 plus: seam gate loads consumed with per-row-group counted vmcnt instead of one vmcnt(0); barrier census loads batched
# baseline (speedup 1.0000x reference)
.Lbr_pf_done:
	s_waitcnt vmcnt(14)
	v_mov_b64_e32 v[150:151], v[176:177]
	s_cmp_lt_i32 s29, 0
	s_mov_b64 s[18:19], -1
	s_cselect_b64 s[20:21], -1, 0
	s_cmp_gt_i32 s29, -1
	v_cvt_f32_ubyte0_e32 v152, v150
	v_cvt_f32_ubyte1_e32 v153, v150
	v_cvt_f32_ubyte2_e32 v154, v150
	v_cvt_f32_ubyte3_e32 v150, v150
	v_cvt_f32_ubyte0_e32 v155, v151
	v_cvt_f32_ubyte1_e32 v156, v151
	v_cvt_f32_ubyte2_e32 v157, v151
	v_cvt_f32_ubyte3_e32 v151, v151
	v_max_f32_e32 v152, v152, v152
	v_max_f32_e32 v153, v153, v153
	v_max_f32_e32 v154, v154, v154
	v_max_f32_e32 v158, v150, v150
	v_max_f32_e32 v155, v155, v155
	v_max_f32_e32 v156, v156, v156
	v_max_f32_e32 v157, v157, v157
	v_max_f32_e32 v159, v151, v151
	v_max_f32_e32 v150, 0x10fd87b6, v152
	v_max_f32_e32 v151, 0x10fd87b6, v153
	v_max_f32_e32 v152, 0x10fd87b6, v154
	v_max_f32_e32 v153, 0x10fd87b6, v158
	v_max_f32_e32 v154, 0x10fd87b6, v155
	v_max_f32_e32 v155, 0x10fd87b6, v156
	v_max_f32_e32 v156, 0x10fd87b6, v157
	v_max_f32_e32 v157, 0x10fd87b6, v159
	s_cbranch_scc1 .LBB0_43
	s_mov_b32 s18, 0x3b808081
	v_pk_mul_f32 v[158:159], v[156:157], s[18:19] op_sel_hi:[1,0]
	v_pk_mul_f32 v[160:161], v[154:155], s[18:19] op_sel_hi:[1,0]
	v_pk_mul_f32 v[162:163], v[152:153], s[18:19] op_sel_hi:[1,0]
	v_pk_mul_f32 v[164:165], v[150:151], s[18:19] op_sel_hi:[1,0]
	s_mov_b64 s[18:19], 0

.LBB0_53:
	s_nop 1
	v_or_b32_e32 v146, 16, v144
	v_ashrrev_i32_e32 v147, 31, v146
	v_readlane_b32 s18, v253, 12
	v_lshlrev_b64 v[148:149], 13, v[146:147]
	v_readlane_b32 s19, v253, 13
	s_and_b64 vcc, exec, s[42:43]
	s_nop 0
	v_lshl_add_u64 v[148:149], s[18:19], 0, v[148:149]
	v_lshl_add_u64 v[150:151], v[148:149], 0, s[16:17]
	v_lshl_add_u64 v[150:151], v[150:151], 0, v[142:143]
	s_waitcnt vmcnt(12)
	v_mov_b64_e32 v[152:153], v[180:181]
	s_mov_b64 s[18:19], -1
	v_cvt_f32_ubyte0_e32 v145, v152
	v_cvt_f32_ubyte1_e32 v154, v152
	v_cvt_f32_ubyte2_e32 v155, v152
	v_cvt_f32_ubyte3_e32 v152, v152
	v_cvt_f32_ubyte0_e32 v156, v153
	v_cvt_f32_ubyte1_e32 v157, v153
	v_cvt_f32_ubyte2_e32 v158, v153
	v_cvt_f32_ubyte3_e32 v153, v153
	v_max_f32_e32 v145, v145, v145
	v_max_f32_e32 v154, v154, v154
	v_max_f32_e32 v155, v155, v155
	v_max_f32_e32 v159, v152, v152
	v_max_f32_e32 v156, v156, v156
	v_max_f32_e32 v157, v157, v157
	v_max_f32_e32 v158, v158, v158
	v_max_f32_e32 v160, v153, v153
	v_max_f32_e32 v152, 0x10fd87b6, v145
	v_max_f32_e32 v153, 0x10fd87b6, v154
	v_max_f32_e32 v154, 0x10fd87b6, v155
	v_max_f32_e32 v155, 0x10fd87b6, v159
	v_max_f32_e32 v156, 0x10fd87b6, v156
	v_max_f32_e32 v157, 0x10fd87b6, v157
	v_max_f32_e32 v158, 0x10fd87b6, v158
	v_max_f32_e32 v159, 0x10fd87b6, v160
	s_cbranch_vccnz .LBB0_55
	s_mov_b32 s18, 0x3b808081
	v_pk_mul_f32 v[160:161], v[158:159], s[18:19] op_sel_hi:[1,0]
	v_pk_mul_f32 v[162:163], v[156:157], s[18:19] op_sel_hi:[1,0]
	v_pk_mul_f32 v[164:165], v[154:155], s[18:19] op_sel_hi:[1,0]
	v_pk_mul_f32 v[166:167], v[152:153], s[18:19] op_sel_hi:[1,0]
	s_mov_b64 s[18:19], 0

.LBB0_65:
	v_or_b32_e32 v146, 32, v144
	v_ashrrev_i32_e32 v147, 31, v146
	v_readlane_b32 s18, v253, 12
	v_lshlrev_b64 v[148:149], 13, v[146:147]
	v_readlane_b32 s19, v253, 13
	s_and_b64 vcc, exec, s[42:43]
	s_nop 0
	v_lshl_add_u64 v[148:149], s[18:19], 0, v[148:149]
	v_lshl_add_u64 v[150:151], v[148:149], 0, s[16:17]
	v_lshl_add_u64 v[150:151], v[150:151], 0, v[142:143]
	s_waitcnt vmcnt(10)
	v_mov_b64_e32 v[152:153], v[184:185]
	s_mov_b64 s[18:19], -1
	v_cvt_f32_ubyte0_e32 v145, v152
	v_cvt_f32_ubyte1_e32 v154, v152
	v_cvt_f32_ubyte2_e32 v155, v152
	v_cvt_f32_ubyte3_e32 v152, v152
	v_cvt_f32_ubyte0_e32 v156, v153
	v_cvt_f32_ubyte1_e32 v157, v153
	v_cvt_f32_ubyte2_e32 v158, v153
	v_cvt_f32_ubyte3_e32 v153, v153
	v_max_f32_e32 v145, v145, v145
	v_max_f32_e32 v154, v154, v154
	v_max_f32_e32 v155, v155, v155
	v_max_f32_e32 v159, v152, v152
	v_max_f32_e32 v156, v156, v156
	v_max_f32_e32 v157, v157, v157
	v_max_f32_e32 v158, v158, v158
	v_max_f32_e32 v160, v153, v153
	v_max_f32_e32 v152, 0x10fd87b6, v145
	v_max_f32_e32 v153, 0x10fd87b6, v154
	v_max_f32_e32 v154, 0x10fd87b6, v155
	v_max_f32_e32 v155, 0x10fd87b6, v159
	v_max_f32_e32 v156, 0x10fd87b6, v156
	v_max_f32_e32 v157, 0x10fd87b6, v157
	v_max_f32_e32 v158, 0x10fd87b6, v158
	v_max_f32_e32 v159, 0x10fd87b6, v160
	s_cbranch_vccnz .LBB0_67
	s_mov_b32 s18, 0x3b808081
	v_pk_mul_f32 v[160:161], v[158:159], s[18:19] op_sel_hi:[1,0]
	v_pk_mul_f32 v[162:163], v[156:157], s[18:19] op_sel_hi:[1,0]
	v_pk_mul_f32 v[164:165], v[154:155], s[18:19] op_sel_hi:[1,0]
	v_pk_mul_f32 v[166:167], v[152:153], s[18:19] op_sel_hi:[1,0]
	s_mov_b64 s[18:19], 0

.LBB0_77:
	v_or_b32_e32 v146, 48, v144
	v_ashrrev_i32_e32 v147, 31, v146
	v_readlane_b32 s18, v253, 12
	v_lshlrev_b64 v[148:149], 13, v[146:147]
	v_readlane_b32 s19, v253, 13
	s_and_b64 vcc, exec, s[42:43]
	s_nop 0
	v_lshl_add_u64 v[148:149], s[18:19], 0, v[148:149]
	v_lshl_add_u64 v[150:151], v[148:149], 0, s[16:17]
	v_lshl_add_u64 v[150:151], v[150:151], 0, v[142:143]
	s_waitcnt vmcnt(8)
	v_mov_b64_e32 v[152:153], v[188:189]
	s_mov_b64 s[18:19], -1
	v_cvt_f32_ubyte0_e32 v145, v152
	v_cvt_f32_ubyte1_e32 v154, v152
	v_cvt_f32_ubyte2_e32 v155, v152
	v_cvt_f32_ubyte3_e32 v152, v152
	v_cvt_f32_ubyte0_e32 v156, v153
	v_cvt_f32_ubyte1_e32 v157, v153
	v_cvt_f32_ubyte2_e32 v158, v153
	v_cvt_f32_ubyte3_e32 v153, v153
	v_max_f32_e32 v145, v145, v145
	v_max_f32_e32 v154, v154, v154
	v_max_f32_e32 v155, v155, v155
	v_max_f32_e32 v159, v152, v152
	v_max_f32_e32 v156, v156, v156
	v_max_f32_e32 v157, v157, v157
	v_max_f32_e32 v158, v158, v158
	v_max_f32_e32 v160, v153, v153
	v_max_f32_e32 v152, 0x10fd87b6, v145
	v_max_f32_e32 v153, 0x10fd87b6, v154
	v_max_f32_e32 v154, 0x10fd87b6, v155
	v_max_f32_e32 v155, 0x10fd87b6, v159
	v_max_f32_e32 v156, 0x10fd87b6, v156
	v_max_f32_e32 v157, 0x10fd87b6, v157
	v_max_f32_e32 v158, 0x10fd87b6, v158
	v_max_f32_e32 v159, 0x10fd87b6, v160
	s_cbranch_vccnz .LBB0_79
	s_mov_b32 s18, 0x3b808081
	v_pk_mul_f32 v[160:161], v[158:159], s[18:19] op_sel_hi:[1,0]
	v_pk_mul_f32 v[162:163], v[156:157], s[18:19] op_sel_hi:[1,0]
	v_pk_mul_f32 v[164:165], v[154:155], s[18:19] op_sel_hi:[1,0]
	v_pk_mul_f32 v[166:167], v[152:153], s[18:19] op_sel_hi:[1,0]
	s_mov_b64 s[18:19], 0

.LBB0_89:
	v_add_u32_e32 v146, 0x80, v144
	v_ashrrev_i32_e32 v147, 31, v146
	v_readlane_b32 s18, v253, 12
	v_lshlrev_b64 v[148:149], 13, v[146:147]
	v_readlane_b32 s19, v253, 13
	s_and_b64 vcc, exec, s[42:43]
	s_nop 0
	v_lshl_add_u64 v[148:149], s[18:19], 0, v[148:149]
	v_lshl_add_u64 v[150:151], v[148:149], 0, s[16:17]
	v_lshl_add_u64 v[150:151], v[150:151], 0, v[142:143]
	s_waitcnt vmcnt(6)
	v_mov_b64_e32 v[152:153], v[192:193]
	s_mov_b64 s[18:19], -1
	v_cvt_f32_ubyte0_e32 v145, v152
	v_cvt_f32_ubyte1_e32 v154, v152
	v_cvt_f32_ubyte2_e32 v155, v152
	v_cvt_f32_ubyte3_e32 v152, v152
	v_cvt_f32_ubyte0_e32 v156, v153
	v_cvt_f32_ubyte1_e32 v157, v153
	v_cvt_f32_ubyte2_e32 v158, v153
	v_cvt_f32_ubyte3_e32 v153, v153
	v_max_f32_e32 v145, v145, v145
	v_max_f32_e32 v154, v154, v154
	v_max_f32_e32 v155, v155, v155
	v_max_f32_e32 v159, v152, v152
	v_max_f32_e32 v156, v156, v156
	v_max_f32_e32 v157, v157, v157
	v_max_f32_e32 v158, v158, v158
	v_max_f32_e32 v160, v153, v153
	v_max_f32_e32 v152, 0x10fd87b6, v145
	v_max_f32_e32 v153, 0x10fd87b6, v154
	v_max_f32_e32 v154, 0x10fd87b6, v155
	v_max_f32_e32 v155, 0x10fd87b6, v159
	v_max_f32_e32 v156, 0x10fd87b6, v156
	v_max_f32_e32 v157, 0x10fd87b6, v157
	v_max_f32_e32 v158, 0x10fd87b6, v158
	v_max_f32_e32 v159, 0x10fd87b6, v160
	s_cbranch_vccnz .LBB0_91
	s_mov_b32 s18, 0x3b808081
	v_pk_mul_f32 v[160:161], v[158:159], s[18:19] op_sel_hi:[1,0]
	v_pk_mul_f32 v[162:163], v[156:157], s[18:19] op_sel_hi:[1,0]
	v_pk_mul_f32 v[164:165], v[154:155], s[18:19] op_sel_hi:[1,0]
	v_pk_mul_f32 v[166:167], v[152:153], s[18:19] op_sel_hi:[1,0]
	s_mov_b64 s[18:19], 0

.LBB0_101:
	v_add_u32_e32 v146, 0x90, v144
	v_ashrrev_i32_e32 v147, 31, v146
	v_readlane_b32 s18, v253, 12
	v_lshlrev_b64 v[148:149], 13, v[146:147]
	v_readlane_b32 s19, v253, 13
	s_and_b64 vcc, exec, s[42:43]
	s_nop 0
	v_lshl_add_u64 v[148:149], s[18:19], 0, v[148:149]
	v_lshl_add_u64 v[150:151], v[148:149], 0, s[16:17]
	v_lshl_add_u64 v[150:151], v[150:151], 0, v[142:143]
	s_waitcnt vmcnt(4)
	v_mov_b64_e32 v[152:153], v[196:197]
	s_mov_b64 s[18:19], -1
	v_cvt_f32_ubyte0_e32 v145, v152
	v_cvt_f32_ubyte1_e32 v154, v152
	v_cvt_f32_ubyte2_e32 v155, v152
	v_cvt_f32_ubyte3_e32 v152, v152
	v_cvt_f32_ubyte0_e32 v156, v153
	v_cvt_f32_ubyte1_e32 v157, v153
	v_cvt_f32_ubyte2_e32 v158, v153
	v_cvt_f32_ubyte3_e32 v153, v153
	v_max_f32_e32 v145, v145, v145
	v_max_f32_e32 v154, v154, v154
	v_max_f32_e32 v155, v155, v155
	v_max_f32_e32 v159, v152, v152
	v_max_f32_e32 v156, v156, v156
	v_max_f32_e32 v157, v157, v157
	v_max_f32_e32 v158, v158, v158
	v_max_f32_e32 v160, v153, v153
	v_max_f32_e32 v152, 0x10fd87b6, v145
	v_max_f32_e32 v153, 0x10fd87b6, v154
	v_max_f32_e32 v154, 0x10fd87b6, v155
	v_max_f32_e32 v155, 0x10fd87b6, v159
	v_max_f32_e32 v156, 0x10fd87b6, v156
	v_max_f32_e32 v157, 0x10fd87b6, v157
	v_max_f32_e32 v158, 0x10fd87b6, v158
	v_max_f32_e32 v159, 0x10fd87b6, v160
	s_cbranch_vccnz .LBB0_103
	s_mov_b32 s18, 0x3b808081
	v_pk_mul_f32 v[160:161], v[158:159], s[18:19] op_sel_hi:[1,0]
	v_pk_mul_f32 v[162:163], v[156:157], s[18:19] op_sel_hi:[1,0]
	v_pk_mul_f32 v[164:165], v[154:155], s[18:19] op_sel_hi:[1,0]
	v_pk_mul_f32 v[166:167], v[152:153], s[18:19] op_sel_hi:[1,0]
	s_mov_b64 s[18:19], 0

.LBB0_113:
	v_add_u32_e32 v146, 0xa0, v144
	v_ashrrev_i32_e32 v147, 31, v146
	v_readlane_b32 s18, v253, 12
	v_lshlrev_b64 v[148:149], 13, v[146:147]
	v_readlane_b32 s19, v253, 13
	s_and_b64 vcc, exec, s[42:43]
	s_nop 0
	v_lshl_add_u64 v[148:149], s[18:19], 0, v[148:149]
	v_lshl_add_u64 v[150:151], v[148:149], 0, s[16:17]
	v_lshl_add_u64 v[150:151], v[150:151], 0, v[142:143]
	s_waitcnt vmcnt(2)
	v_mov_b64_e32 v[152:153], v[200:201]
	s_mov_b64 s[18:19], -1
	v_cvt_f32_ubyte0_e32 v145, v152
	v_cvt_f32_ubyte1_e32 v154, v152
	v_cvt_f32_ubyte2_e32 v155, v152
	v_cvt_f32_ubyte3_e32 v152, v152
	v_cvt_f32_ubyte0_e32 v156, v153
	v_cvt_f32_ubyte1_e32 v157, v153
	v_cvt_f32_ubyte2_e32 v158, v153
	v_cvt_f32_ubyte3_e32 v153, v153
	v_max_f32_e32 v145, v145, v145
	v_max_f32_e32 v154, v154, v154
	v_max_f32_e32 v155, v155, v155
	v_max_f32_e32 v159, v152, v152
	v_max_f32_e32 v156, v156, v156
	v_max_f32_e32 v157, v157, v157
	v_max_f32_e32 v158, v158, v158
	v_max_f32_e32 v160, v153, v153
	v_max_f32_e32 v152, 0x10fd87b6, v145
	v_max_f32_e32 v153, 0x10fd87b6, v154
	v_max_f32_e32 v154, 0x10fd87b6, v155
	v_max_f32_e32 v155, 0x10fd87b6, v159
	v_max_f32_e32 v156, 0x10fd87b6, v156
	v_max_f32_e32 v157, 0x10fd87b6, v157
	v_max_f32_e32 v158, 0x10fd87b6, v158
	v_max_f32_e32 v159, 0x10fd87b6, v160
	s_cbranch_vccnz .LBB0_115
	s_mov_b32 s18, 0x3b808081
	v_pk_mul_f32 v[160:161], v[158:159], s[18:19] op_sel_hi:[1,0]
	v_pk_mul_f32 v[162:163], v[156:157], s[18:19] op_sel_hi:[1,0]
	v_pk_mul_f32 v[164:165], v[154:155], s[18:19] op_sel_hi:[1,0]
	v_pk_mul_f32 v[166:167], v[152:153], s[18:19] op_sel_hi:[1,0]
	s_mov_b64 s[18:19], 0

.LBB0_125:
	v_add_u32_e32 v144, 0xb0, v144
	v_ashrrev_i32_e32 v145, 31, v144
	v_readlane_b32 s18, v253, 12
	v_lshlrev_b64 v[146:147], 13, v[144:145]
	v_readlane_b32 s19, v253, 13
	s_and_b64 vcc, exec, s[42:43]
	s_nop 0
	v_lshl_add_u64 v[146:147], s[18:19], 0, v[146:147]
	v_lshl_add_u64 v[148:149], v[146:147], 0, s[16:17]
	v_lshl_add_u64 v[148:149], v[148:149], 0, v[142:143]
	s_waitcnt vmcnt(0)
	v_mov_b64_e32 v[150:151], v[204:205]
	s_mov_b64 s[16:17], -1
	v_cvt_f32_ubyte0_e32 v152, v150
	v_cvt_f32_ubyte1_e32 v153, v150
	v_cvt_f32_ubyte2_e32 v154, v150
	v_cvt_f32_ubyte3_e32 v150, v150
	v_cvt_f32_ubyte0_e32 v155, v151
	v_cvt_f32_ubyte1_e32 v156, v151
	v_cvt_f32_ubyte2_e32 v157, v151
	v_cvt_f32_ubyte3_e32 v151, v151
	v_max_f32_e32 v152, v152, v152
	v_max_f32_e32 v153, v153, v153
	v_max_f32_e32 v154, v154, v154
	v_max_f32_e32 v158, v150, v150
	v_max_f32_e32 v155, v155, v155
	v_max_f32_e32 v156, v156, v156
	v_max_f32_e32 v157, v157, v157
	v_max_f32_e32 v159, v151, v151
	v_max_f32_e32 v150, 0x10fd87b6, v152
	v_max_f32_e32 v151, 0x10fd87b6, v153
	v_max_f32_e32 v152, 0x10fd87b6, v154
	v_max_f32_e32 v153, 0x10fd87b6, v158
	v_max_f32_e32 v154, 0x10fd87b6, v155
	v_max_f32_e32 v155, 0x10fd87b6, v156
	v_max_f32_e32 v156, 0x10fd87b6, v157
	v_max_f32_e32 v157, 0x10fd87b6, v159
	s_cbranch_vccnz .LBB0_127
	s_mov_b32 s16, 0x3b808081
	v_pk_mul_f32 v[158:159], v[156:157], s[16:17] op_sel_hi:[1,0]
	v_pk_mul_f32 v[160:161], v[154:155], s[16:17] op_sel_hi:[1,0]
	v_pk_mul_f32 v[162:163], v[152:153], s[16:17] op_sel_hi:[1,0]
	v_pk_mul_f32 v[164:165], v[150:151], s[16:17] op_sel_hi:[1,0]
	s_mov_b64 s[16:17], 0

.LBB0_1227:
	v_readlane_b32 s2, v253, 32
	v_readlane_b32 s3, v253, 33
	s_mov_b64 s[4:5], -1
	s_nop 3
	global_load_dword v0, v1, s[2:3] sc1
	v_readlane_b32 s2, v253, 34
	v_readlane_b32 s3, v253, 35
	s_waitcnt lgkmcnt(0)
	s_nop 3
	global_load_dword v2, v1, s[2:3] sc1
	v_readlane_b32 s2, v253, 36
	v_readlane_b32 s3, v253, 37
	s_nop 4
	global_load_dword v3, v1, s[2:3] sc1
	v_readlane_b32 s2, v253, 38
	v_readlane_b32 s3, v253, 39
	s_nop 4
	global_load_dword v4, v1, s[2:3] sc1
	v_readlane_b32 s2, v253, 40
	v_readlane_b32 s3, v253, 41
	s_nop 4
	global_load_dword v5, v1, s[2:3] sc1
	v_readlane_b32 s2, v253, 42
	v_readlane_b32 s3, v253, 43
	s_nop 4
	global_load_dword v6, v1, s[2:3] sc1
	v_readlane_b32 s2, v253, 44
	v_readlane_b32 s3, v253, 45
	s_nop 4
	global_load_dword v7, v1, s[2:3] sc1
	v_readlane_b32 s2, v253, 46
	v_readlane_b32 s3, v253, 47
	s_nop 4
	global_load_dword v8, v1, s[2:3] sc1
	v_readlane_b32 s2, v253, 48
	v_readlane_b32 s3, v253, 49
	s_nop 4
	global_load_dword v9, v1, s[2:3] sc1
	v_readlane_b32 s2, v253, 50
	v_readlane_b32 s3, v253, 51
	s_nop 4
	global_load_dword v10, v1, s[2:3] sc1
	v_readlane_b32 s2, v253, 52
	v_readlane_b32 s3, v253, 53
	s_nop 4
	global_load_dword v11, v1, s[2:3] sc1
	v_readlane_b32 s2, v253, 54
	v_readlane_b32 s3, v253, 55
	s_nop 4
	global_load_dword v12, v1, s[2:3] sc1
	v_readlane_b32 s2, v253, 56
	v_readlane_b32 s3, v253, 57
	s_nop 4
	global_load_dword v13, v1, s[2:3] sc1
	v_readlane_b32 s2, v253, 58
	v_readlane_b32 s3, v253, 59
	s_nop 4
	global_load_dword v14, v1, s[2:3] sc1
	v_readlane_b32 s2, v253, 60
	v_readlane_b32 s3, v253, 61
	s_nop 4
	global_load_dword v15, v1, s[2:3] sc1
	v_readlane_b32 s2, v253, 62
	v_readlane_b32 s3, v253, 63
	s_nop 4
	global_load_dword v17, v1, s[2:3] sc1
	s_mov_b64 s[2:3], -1
	s_waitcnt vmcnt(0)
	v_add_u32_e32 v18, v2, v0
	v_add_u32_e32 v18, v18, v3
	v_add_u32_e32 v18, v18, v4
	v_add_u32_e32 v18, v18, v5
	v_add_u32_e32 v18, v18, v6
	v_add_u32_e32 v18, v18, v7
	v_add_u32_e32 v18, v18, v8
	v_add_u32_e32 v18, v18, v9
	v_add_u32_e32 v18, v18, v10
	v_add_u32_e32 v18, v18, v11
	v_add_u32_e32 v18, v18, v12
	v_add_u32_e32 v18, v18, v13
	v_add_u32_e32 v18, v18, v14
	v_add_u32_e32 v18, v18, v15
	v_add_u32_e32 v18, v18, v17
	v_cmp_eq_u32_e32 vcc, s93, v18
	s_cbranch_vccnz .LBB0_1226
	s_and_b32 s2, s8, 0xff
	s_cmp_eq_u32 s2, 0
	s_mov_b64 s[2:3], -1
	s_mov_b64 s[6:7], -1
	s_sleep 1
	s_cbranch_scc1 .LBB0_1231
	s_and_b64 vcc, exec, s[6:7]
	s_cbranch_vccz .LBB0_1226
